# P0 x->bf16 conversion loop hand-rewritten (double-buffered slots, counted waits never cover stores); fold workgroups convert no x slot
# baseline (speedup 1.0000x reference)
.LBB0_38:
	s_add_u32 s24, s64, 0x2400000
	s_mul_i32 s0, s36, 5
	s_addc_u32 s25, s65, 0
	s_add_i32 s3, s0, s12
	s_and_b64 s[0:1], s[4:5], exec
	s_mul_i32 s0, s13, 5
	s_cselect_b32 s3, s66, s3
	s_add_i32 s4, s0, s12
	s_ashr_i32 s5, s4, 31
	s_lshl_b64 s[8:9], s[4:5], 10
	s_lshl_b64 s[14:15], s[4:5], 11
	s_lshl_b64 s[0:1], s[4:5], 9
	s_lshl_b64 s[18:19], s[4:5], 12
	s_mul_i32 s9, s4, 0x600
	s_mul_i32 s15, s4, 0xc00
	v_mov_b32_e32 v14, 0
	s_mov_b32 s34, 0x7fff80
	s_mov_b64 s[20:21], 0x200
	s_mov_b64 s[36:37], 0x3fffff
	s_mov_b32 s40, s3
	s_cmpk_eq_i32 s4, 0x480
	s_cbranch_scc0 .LBB0_40
	s_cmp_eq_u32 s38, 1
	s_cbranch_scc1 .LBB0_55
	s_sub_i32 s7, s66, 32
	s_cmpk_lt_u32 s7, 0x20
	s_cselect_b32 s38, 6, 5
	s_sub_i32 s0, s7, s3
	s_add_i32 s0, s0, -4
	s_lshl_b32 s9, s0, 13
	s_lshl_b32 s8, s0, 14
	v_and_b32_e32 v1, 63, v130
	v_lshrrev_b32_e32 v2, 6, v130
	v_lshl_or_b32 v1, v2, 7, v1
	v_lshlrev_b32_e32 v14, 4, v1
	v_lshlrev_b32_e32 v15, 3, v1
	s_lshl_b32 s0, s3, 14
	s_lshl_b32 s1, s3, 13
	v_add_u32_e32 v2, s0, v14
	v_add_u32_e32 v3, s1, v15
	s_mov_b32 s35, 0
	global_load_dwordx4 v[16:19], v2, s[16:17] nt
	global_load_dwordx4 v[20:23], v2, s[16:17] offset:1024 nt
	v_add_u32_e32 v5, 0x1200000, v2
	global_load_dwordx4 v[24:27], v5, s[16:17] nt
	global_load_dwordx4 v[28:31], v5, s[16:17] offset:1024 nt
	v_add_u32_e32 v6, 0x2400000, v2
	global_load_dwordx4 v[32:35], v6, s[16:17] nt
	global_load_dwordx4 v[36:39], v6, s[16:17] offset:1024 nt
	v_add_u32_e32 v7, 0x3600000, v2
	global_load_dwordx4 v[40:43], v7, s[16:17] nt
	global_load_dwordx4 v[44:47], v7, s[16:17] offset:1024 nt
	v_add_u32_e32 v8, 0x4800000, v2
	global_load_dwordx4 v[48:51], v8, s[16:17] nt
	global_load_dwordx4 v[52:55], v8, s[16:17] offset:1024 nt
	v_add_u32_e32 v9, 0x5a00000, v2
	global_load_dwordx4 v[56:59], v9, s[16:17] nt
	global_load_dwordx4 v[60:63], v9, s[16:17] offset:1024 nt
	v_add_u32_e32 v10, 0x6c00000, v2
	global_load_dwordx4 v[64:67], v10, s[16:17] nt
	global_load_dwordx4 v[68:71], v10, s[16:17] offset:1024 nt
.Lxf_A:
	s_add_i32 s0, s35, 1
	s_cmp_lt_u32 s0, s38
	s_cbranch_scc0 .Lxf_A_last
	s_cmp_eq_u32 s35, 4
	s_cselect_b32 s6, s8, 0x4000
	v_add_u32_e32 v2, s6, v2
	global_load_dwordx4 v[72:75], v2, s[16:17] nt
	global_load_dwordx4 v[76:79], v2, s[16:17] offset:1024 nt
	v_add_u32_e32 v5, 0x1200000, v2
	global_load_dwordx4 v[80:83], v5, s[16:17] nt
	global_load_dwordx4 v[84:87], v5, s[16:17] offset:1024 nt
	v_add_u32_e32 v6, 0x2400000, v2
	global_load_dwordx4 v[88:91], v6, s[16:17] nt
	global_load_dwordx4 v[92:95], v6, s[16:17] offset:1024 nt
	v_add_u32_e32 v7, 0x3600000, v2
	global_load_dwordx4 v[96:99], v7, s[16:17] nt
	global_load_dwordx4 v[100:103], v7, s[16:17] offset:1024 nt
	v_add_u32_e32 v8, 0x4800000, v2
	global_load_dwordx4 v[104:107], v8, s[16:17] nt
	global_load_dwordx4 v[108:111], v8, s[16:17] offset:1024 nt
	v_add_u32_e32 v9, 0x5a00000, v2
	global_load_dwordx4 v[112:115], v9, s[16:17] nt
	global_load_dwordx4 v[116:119], v9, s[16:17] offset:1024 nt
	v_add_u32_e32 v10, 0x6c00000, v2
	global_load_dwordx4 v[120:123], v10, s[16:17] nt
	global_load_dwordx4 v[124:127], v10, s[16:17] offset:1024 nt
	s_cmp_eq_u32 s35, 0
	s_cbranch_scc1 .Lxf_A_w14
	s_waitcnt vmcnt(28)
	s_branch .Lxf_A_go
.Lxf_A_w14:
	s_waitcnt vmcnt(14)
	s_branch .Lxf_A_go
.Lxf_A_last:
	s_cmp_eq_u32 s35, 0
	s_cbranch_scc1 .Lxf_A_w0
	s_waitcnt vmcnt(14)
	s_branch .Lxf_A_go

.Lxf_A_go:
	v_cvt_pk_bf16_f32 v16, v16, v17
	v_cvt_pk_bf16_f32 v17, v18, v19
	v_cvt_pk_bf16_f32 v20, v20, v21
	v_cvt_pk_bf16_f32 v21, v22, v23
	global_store_dwordx2 v3, v[16:17], s[24:25] sc0 sc1
	global_store_dwordx2 v3, v[20:21], s[24:25] offset:512 sc0 sc1
	v_cvt_pk_bf16_f32 v24, v24, v25
	v_cvt_pk_bf16_f32 v25, v26, v27
	v_cvt_pk_bf16_f32 v28, v28, v29
	v_cvt_pk_bf16_f32 v29, v30, v31
	v_add_u32_e32 v5, 0x900000, v3
	global_store_dwordx2 v5, v[24:25], s[24:25] sc0 sc1
	global_store_dwordx2 v5, v[28:29], s[24:25] offset:512 sc0 sc1
	v_cvt_pk_bf16_f32 v32, v32, v33
	v_cvt_pk_bf16_f32 v33, v34, v35
	v_cvt_pk_bf16_f32 v36, v36, v37
	v_cvt_pk_bf16_f32 v37, v38, v39
	v_add_u32_e32 v6, 0x1200000, v3
	global_store_dwordx2 v6, v[32:33], s[24:25] sc0 sc1
	global_store_dwordx2 v6, v[36:37], s[24:25] offset:512 sc0 sc1
	v_cvt_pk_bf16_f32 v40, v40, v41
	v_cvt_pk_bf16_f32 v41, v42, v43
	v_cvt_pk_bf16_f32 v44, v44, v45
	v_cvt_pk_bf16_f32 v45, v46, v47
	v_add_u32_e32 v7, 0x1b00000, v3
	global_store_dwordx2 v7, v[40:41], s[24:25] sc0 sc1
	global_store_dwordx2 v7, v[44:45], s[24:25] offset:512 sc0 sc1
	v_cvt_pk_bf16_f32 v48, v48, v49
	v_cvt_pk_bf16_f32 v49, v50, v51
	v_cvt_pk_bf16_f32 v52, v52, v53
	v_cvt_pk_bf16_f32 v53, v54, v55
	v_add_u32_e32 v8, 0x2400000, v3
	global_store_dwordx2 v8, v[48:49], s[24:25] sc0 sc1
	global_store_dwordx2 v8, v[52:53], s[24:25] offset:512 sc0 sc1
	v_cvt_pk_bf16_f32 v56, v56, v57
	v_cvt_pk_bf16_f32 v57, v58, v59
	v_cvt_pk_bf16_f32 v60, v60, v61
	v_cvt_pk_bf16_f32 v61, v62, v63
	v_add_u32_e32 v9, 0x2d00000, v3
	global_store_dwordx2 v9, v[56:57], s[24:25] sc0 sc1
	global_store_dwordx2 v9, v[60:61], s[24:25] offset:512 sc0 sc1
	v_cvt_pk_bf16_f32 v64, v64, v65
	v_cvt_pk_bf16_f32 v65, v66, v67
	v_cvt_pk_bf16_f32 v68, v68, v69
	v_cvt_pk_bf16_f32 v69, v70, v71
	v_add_u32_e32 v10, 0x3600000, v3
	global_store_dwordx2 v10, v[64:65], s[24:25] sc0 sc1
	global_store_dwordx2 v10, v[68:69], s[24:25] offset:512 sc0 sc1
	s_cmp_eq_u32 s35, 4
	s_cselect_b32 s6, s9, 0x2000
	v_add_u32_e32 v3, s6, v3
	s_add_i32 s35, s35, 1
	s_cmp_lt_u32 s35, s38
	s_cbranch_scc1 .Lxf_B
	s_branch .Lxf_tail
.Lxf_B:
	s_add_i32 s0, s35, 1
	s_cmp_lt_u32 s0, s38
	s_cbranch_scc0 .Lxf_B_last
	s_cmp_eq_u32 s35, 4
	s_cselect_b32 s6, s8, 0x4000
	v_add_u32_e32 v2, s6, v2
	global_load_dwordx4 v[16:19], v2, s[16:17] nt
	global_load_dwordx4 v[20:23], v2, s[16:17] offset:1024 nt
	v_add_u32_e32 v5, 0x1200000, v2
	global_load_dwordx4 v[24:27], v5, s[16:17] nt
	global_load_dwordx4 v[28:31], v5, s[16:17] offset:1024 nt
	v_add_u32_e32 v6, 0x2400000, v2
	global_load_dwordx4 v[32:35], v6, s[16:17] nt
	global_load_dwordx4 v[36:39], v6, s[16:17] offset:1024 nt
	v_add_u32_e32 v7, 0x3600000, v2
	global_load_dwordx4 v[40:43], v7, s[16:17] nt
	global_load_dwordx4 v[44:47], v7, s[16:17] offset:1024 nt
	v_add_u32_e32 v8, 0x4800000, v2
	global_load_dwordx4 v[48:51], v8, s[16:17] nt
	global_load_dwordx4 v[52:55], v8, s[16:17] offset:1024 nt
	v_add_u32_e32 v9, 0x5a00000, v2
	global_load_dwordx4 v[56:59], v9, s[16:17] nt
	global_load_dwordx4 v[60:63], v9, s[16:17] offset:1024 nt
	v_add_u32_e32 v10, 0x6c00000, v2
	global_load_dwordx4 v[64:67], v10, s[16:17] nt
	global_load_dwordx4 v[68:71], v10, s[16:17] offset:1024 nt
	s_waitcnt vmcnt(28)
	s_branch .Lxf_B_go
.Lxf_B_last:
	s_waitcnt vmcnt(14)
.Lxf_B_go:
	v_cvt_pk_bf16_f32 v72, v72, v73
	v_cvt_pk_bf16_f32 v73, v74, v75
	v_cvt_pk_bf16_f32 v76, v76, v77
	v_cvt_pk_bf16_f32 v77, v78, v79
	global_store_dwordx2 v3, v[72:73], s[24:25] sc0 sc1
	global_store_dwordx2 v3, v[76:77], s[24:25] offset:512 sc0 sc1
	v_cvt_pk_bf16_f32 v80, v80, v81
	v_cvt_pk_bf16_f32 v81, v82, v83
	v_cvt_pk_bf16_f32 v84, v84, v85
	v_cvt_pk_bf16_f32 v85, v86, v87
	v_add_u32_e32 v5, 0x900000, v3
	global_store_dwordx2 v5, v[80:81], s[24:25] sc0 sc1
	global_store_dwordx2 v5, v[84:85], s[24:25] offset:512 sc0 sc1
	v_cvt_pk_bf16_f32 v88, v88, v89
	v_cvt_pk_bf16_f32 v89, v90, v91
	v_cvt_pk_bf16_f32 v92, v92, v93
	v_cvt_pk_bf16_f32 v93, v94, v95
	v_add_u32_e32 v6, 0x1200000, v3
	global_store_dwordx2 v6, v[88:89], s[24:25] sc0 sc1
	global_store_dwordx2 v6, v[92:93], s[24:25] offset:512 sc0 sc1
	v_cvt_pk_bf16_f32 v96, v96, v97
	v_cvt_pk_bf16_f32 v97, v98, v99
	v_cvt_pk_bf16_f32 v100, v100, v101
	v_cvt_pk_bf16_f32 v101, v102, v103
	v_add_u32_e32 v7, 0x1b00000, v3
	global_store_dwordx2 v7, v[96:97], s[24:25] sc0 sc1
	global_store_dwordx2 v7, v[100:101], s[24:25] offset:512 sc0 sc1
	v_cvt_pk_bf16_f32 v104, v104, v105
	v_cvt_pk_bf16_f32 v105, v106, v107
	v_cvt_pk_bf16_f32 v108, v108, v109
	v_cvt_pk_bf16_f32 v109, v110, v111
	v_add_u32_e32 v8, 0x2400000, v3
	global_store_dwordx2 v8, v[104:105], s[24:25] sc0 sc1
	global_store_dwordx2 v8, v[108:109], s[24:25] offset:512 sc0 sc1
	v_cvt_pk_bf16_f32 v112, v112, v113
	v_cvt_pk_bf16_f32 v113, v114, v115
	v_cvt_pk_bf16_f32 v116, v116, v117
	v_cvt_pk_bf16_f32 v117, v118, v119
	v_add_u32_e32 v9, 0x2d00000, v3
	global_store_dwordx2 v9, v[112:113], s[24:25] sc0 sc1
	global_store_dwordx2 v9, v[116:117], s[24:25] offset:512 sc0 sc1
	v_cvt_pk_bf16_f32 v120, v120, v121
	v_cvt_pk_bf16_f32 v121, v122, v123
	v_cvt_pk_bf16_f32 v124, v124, v125
	v_cvt_pk_bf16_f32 v125, v126, v127
	v_add_u32_e32 v10, 0x3600000, v3
	global_store_dwordx2 v10, v[120:121], s[24:25] sc0 sc1
	global_store_dwordx2 v10, v[124:125], s[24:25] offset:512 sc0 sc1
	s_cmp_eq_u32 s35, 4
	s_cselect_b32 s6, s9, 0x2000
	v_add_u32_e32 v3, s6, v3
	s_add_i32 s35, s35, 1
	s_cmp_lt_u32 s35, s38
	s_cbranch_scc1 .Lxf_A
.Lxf_tail:
	s_add_i32 s0, s3, 0
	s_cmpk_lt_u32 s0, 0x80
	s_cbranch_scc0 .Lxf_tl0
	s_lshl_b32 s0, s0, 14
	v_add_u32_e32 v4, s0, v14
	v_add_u32_e32 v4, 0x7e00000, v4
	global_load_dwordx4 v[16:19], v4, s[16:17] nt
	global_load_dwordx4 v[20:23], v4, s[16:17] offset:1024 nt
.Lxf_tl0:
	s_add_i32 s0, s3, 1
	s_cmpk_lt_u32 s0, 0x80
	s_cbranch_scc0 .Lxf_tl1
	s_lshl_b32 s0, s0, 14
	v_add_u32_e32 v4, s0, v14
	v_add_u32_e32 v4, 0x7e00000, v4
	global_load_dwordx4 v[24:27], v4, s[16:17] nt
	global_load_dwordx4 v[28:31], v4, s[16:17] offset:1024 nt
.Lxf_tl1:
	s_add_i32 s0, s3, 2
	s_cmpk_lt_u32 s0, 0x80
	s_cbranch_scc0 .Lxf_tl2
	s_lshl_b32 s0, s0, 14
	v_add_u32_e32 v4, s0, v14
	v_add_u32_e32 v4, 0x7e00000, v4
	global_load_dwordx4 v[32:35], v4, s[16:17] nt
	global_load_dwordx4 v[36:39], v4, s[16:17] offset:1024 nt
.Lxf_tl2:
	s_add_i32 s0, s3, 3
	s_cmpk_lt_u32 s0, 0x80
	s_cbranch_scc0 .Lxf_tl3
	s_lshl_b32 s0, s0, 14
	v_add_u32_e32 v4, s0, v14
	v_add_u32_e32 v4, 0x7e00000, v4
	global_load_dwordx4 v[40:43], v4, s[16:17] nt
	global_load_dwordx4 v[44:47], v4, s[16:17] offset:1024 nt
.Lxf_tl3:
	s_add_i32 s0, s3, 4
	s_cmpk_lt_u32 s0, 0x80
	s_cbranch_scc0 .Lxf_tl4
	s_lshl_b32 s0, s0, 14
	v_add_u32_e32 v4, s0, v14
	v_add_u32_e32 v4, 0x7e00000, v4
	global_load_dwordx4 v[48:51], v4, s[16:17] nt
	global_load_dwordx4 v[52:55], v4, s[16:17] offset:1024 nt
.Lxf_tl4:
	s_cmp_eq_u32 s38, 6
	s_cbranch_scc0 .Lxf_tl5
	s_mov_b32 s0, s7
	s_lshl_b32 s0, s0, 14
	v_add_u32_e32 v4, s0, v14
	v_add_u32_e32 v4, 0x7e00000, v4
	global_load_dwordx4 v[56:59], v4, s[16:17] nt
	global_load_dwordx4 v[60:63], v4, s[16:17] offset:1024 nt
.Lxf_tl5:
	s_waitcnt vmcnt(0)
	s_add_i32 s0, s3, 0
	s_cmpk_lt_u32 s0, 0x80
	s_cbranch_scc0 .Lxf_ts0
	s_lshl_b32 s0, s0, 13
	v_cvt_pk_bf16_f32 v16, v16, v17
	v_cvt_pk_bf16_f32 v17, v18, v19
	v_cvt_pk_bf16_f32 v20, v20, v21
	v_cvt_pk_bf16_f32 v21, v22, v23
	v_add_u32_e32 v4, s0, v15
	v_add_u32_e32 v4, 0x3f00000, v4
	global_store_dwordx2 v4, v[16:17], s[24:25] sc0 sc1
	global_store_dwordx2 v4, v[20:21], s[24:25] offset:512 sc0 sc1
.Lxf_ts0:
	s_add_i32 s0, s3, 1
	s_cmpk_lt_u32 s0, 0x80
	s_cbranch_scc0 .Lxf_ts1
	s_lshl_b32 s0, s0, 13
	v_cvt_pk_bf16_f32 v24, v24, v25
	v_cvt_pk_bf16_f32 v25, v26, v27
	v_cvt_pk_bf16_f32 v28, v28, v29
	v_cvt_pk_bf16_f32 v29, v30, v31
	v_add_u32_e32 v4, s0, v15
	v_add_u32_e32 v4, 0x3f00000, v4
	global_store_dwordx2 v4, v[24:25], s[24:25] sc0 sc1
	global_store_dwordx2 v4, v[28:29], s[24:25] offset:512 sc0 sc1
.Lxf_ts1:
	s_add_i32 s0, s3, 2
	s_cmpk_lt_u32 s0, 0x80
	s_cbranch_scc0 .Lxf_ts2
	s_lshl_b32 s0, s0, 13
	v_cvt_pk_bf16_f32 v32, v32, v33
	v_cvt_pk_bf16_f32 v33, v34, v35
	v_cvt_pk_bf16_f32 v36, v36, v37
	v_cvt_pk_bf16_f32 v37, v38, v39
	v_add_u32_e32 v4, s0, v15
	v_add_u32_e32 v4, 0x3f00000, v4
	global_store_dwordx2 v4, v[32:33], s[24:25] sc0 sc1
	global_store_dwordx2 v4, v[36:37], s[24:25] offset:512 sc0 sc1
.Lxf_ts2:
	s_add_i32 s0, s3, 3
	s_cmpk_lt_u32 s0, 0x80
	s_cbranch_scc0 .Lxf_ts3
	s_lshl_b32 s0, s0, 13
	v_cvt_pk_bf16_f32 v40, v40, v41
	v_cvt_pk_bf16_f32 v41, v42, v43
	v_cvt_pk_bf16_f32 v44, v44, v45
	v_cvt_pk_bf16_f32 v45, v46, v47
	v_add_u32_e32 v4, s0, v15
	v_add_u32_e32 v4, 0x3f00000, v4
	global_store_dwordx2 v4, v[40:41], s[24:25] sc0 sc1
	global_store_dwordx2 v4, v[44:45], s[24:25] offset:512 sc0 sc1
.Lxf_ts3:
	s_add_i32 s0, s3, 4
	s_cmpk_lt_u32 s0, 0x80
	s_cbranch_scc0 .Lxf_ts4
	s_lshl_b32 s0, s0, 13
	v_cvt_pk_bf16_f32 v48, v48, v49
	v_cvt_pk_bf16_f32 v49, v50, v51
	v_cvt_pk_bf16_f32 v52, v52, v53
	v_cvt_pk_bf16_f32 v53, v54, v55
	v_add_u32_e32 v4, s0, v15
	v_add_u32_e32 v4, 0x3f00000, v4
	global_store_dwordx2 v4, v[48:49], s[24:25] sc0 sc1
	global_store_dwordx2 v4, v[52:53], s[24:25] offset:512 sc0 sc1
.Lxf_ts4:
	s_cmp_eq_u32 s38, 6
	s_cbranch_scc0 .Lxf_ts5
	s_mov_b32 s0, s7
	s_lshl_b32 s0, s0, 13
	v_cvt_pk_bf16_f32 v56, v56, v57
	v_cvt_pk_bf16_f32 v57, v58, v59
	v_cvt_pk_bf16_f32 v60, v60, v61
	v_cvt_pk_bf16_f32 v61, v62, v63
	v_add_u32_e32 v4, s0, v15
	v_add_u32_e32 v4, 0x3f00000, v4
	global_store_dwordx2 v4, v[56:57], s[24:25] sc0 sc1
	global_store_dwordx2 v4, v[60:61], s[24:25] offset:512 sc0 sc1
.Lxf_ts5:
	s_branch .LBB0_55
